# score loop: sync block (wait+barrier+DMA+fragment reads) placed behind the second sub-tile instead of the first
# baseline (speedup 1.0000x reference)
; #define MFMA(a, b, c) __builtin_amdgcn_mfma_f32_32x32x16_bf16((a), (b), (c), 0, 0, 0)
; DI void score_phase(const Params& p, char* smem) {
;     ...
;     for (int nt2 = nt_lo; nt2 < nt_hi; ++nt2) {
;       const int k0 = nt2 * 32;
;       const int kn = (nt2 + 1 < nt_hi) ? (k0 + 32) : k0;
; #pragma unroll
;       for (int st = 0; st < 4; ++st) bnx[st] = *(const bf16x8*)(Hb + (size_t)(kn + r) * HLD + 4096 + st * 16 + 8 * h);
; #pragma unroll
;       for (int rt = 0; rt < 4; ++rt) {
;         f32x16 acc;
; #pragma unroll
;         for (int e = 0; e < 16; ++e) acc[e] = 0.f;
; #pragma unroll
;         for (int st = 0; st < 4; ++st) acc = MFMA(af[rt][st], bfr[st], acc);
;         float s = 0.f;
; #pragma unroll
;         for (int e4 = 0; e4 < 4; ++e4) {
;           const f32x4 wv = *(const f32x4*)(wl + (2 * rt + h) * 16 + e4 * 4);
; #pragma unroll
;           for (int i = 0; i < 4; ++i) s += fmaxf(acc[e4 * 4 + i], 0.f) * wv[i];
;         }
;         const int row = (t0 + 2 * rt + h) - blk * 64;
;         __builtin_nontemporal_store(s, scb + (size_t)row * n + k0 + r);
;       }
; #pragma unroll
;       for (int st = 0; st < 4; ++st) bfr[st] = bnx[st];
.LBB0_822:
	s_add_i32 s15, s15, 1
	s_add_i32 s17, s8, 32
	s_add_i32 s19, s8, 96
	s_add_i32 s18, s15, 2
	s_cmp_lt_i32 s18, s16
	s_cselect_b32 s18, s19, s8
	s_ashr_i32 s9, s8, 31
	v_lshl_add_u64 v[196:197], s[8:9], 2, v[186:187]
	s_mov_b32 s8, s17
	v_mfma_f32_32x32x16_bf16 v[224:239], v[42:45], v[174:177], 0
	v_max_f32_e32 v240, 0, v2
	v_fma_f32 v183, v82, v240, 0
	v_max_f32_e32 v241, 0, v3
	v_fmac_f32_e32 v183, v83, v241
	v_max_f32_e32 v240, 0, v4
	v_fmac_f32_e32 v183, v84, v240
	v_max_f32_e32 v241, 0, v5
	v_fmac_f32_e32 v183, v85, v241
	v_mfma_f32_32x32x16_bf16 v[224:239], v[34:37], v[170:173], v[224:239]
	v_max_f32_e32 v240, 0, v6
	v_fmac_f32_e32 v183, v86, v240
	v_max_f32_e32 v241, 0, v7
	v_fmac_f32_e32 v183, v87, v241
	v_max_f32_e32 v240, 0, v8
	v_fmac_f32_e32 v183, v88, v240
	v_max_f32_e32 v241, 0, v9
	v_fmac_f32_e32 v183, v89, v241
	v_mfma_f32_32x32x16_bf16 v[224:239], v[38:41], v[166:169], v[224:239]
	v_max_f32_e32 v240, 0, v10
	v_fmac_f32_e32 v183, v90, v240
	v_max_f32_e32 v241, 0, v11
	v_fmac_f32_e32 v183, v91, v241
	v_max_f32_e32 v240, 0, v12
	v_fmac_f32_e32 v183, v92, v240
	v_max_f32_e32 v241, 0, v13
	v_fmac_f32_e32 v183, v93, v241
	v_mfma_f32_32x32x16_bf16 v[224:239], v[46:49], v[162:165], v[224:239]
	v_max_f32_e32 v240, 0, v14
	v_fmac_f32_e32 v183, v94, v240
	v_max_f32_e32 v241, 0, v15
	v_fmac_f32_e32 v183, v95, v241
	v_max_f32_e32 v240, 0, v16
	v_fmac_f32_e32 v183, v96, v240
	v_max_f32_e32 v241, 0, v17
	v_fmac_f32_e32 v183, v97, v241
	v_lshl_add_u64 v[242:243], v[188:189], 2, v[196:197]
	global_store_dword v[242:243], v183, off nt
	s_nop 1
	v_mfma_f32_32x32x16_bf16 v[2:17], v[58:61], v[174:177], 0
	v_max_f32_e32 v240, 0, v224
	v_fma_f32 v183, v98, v240, 0
	v_max_f32_e32 v241, 0, v225
	v_fmac_f32_e32 v183, v99, v241
	v_max_f32_e32 v240, 0, v226
	v_fmac_f32_e32 v183, v100, v240
	v_max_f32_e32 v241, 0, v227
	v_fmac_f32_e32 v183, v101, v241
	v_mfma_f32_32x32x16_bf16 v[2:17], v[50:53], v[170:173], v[2:17]
	v_max_f32_e32 v240, 0, v228
	v_fmac_f32_e32 v183, v102, v240
	v_max_f32_e32 v241, 0, v229
	v_fmac_f32_e32 v183, v103, v241
	v_max_f32_e32 v240, 0, v230
	v_fmac_f32_e32 v183, v104, v240
	v_max_f32_e32 v241, 0, v231
	v_fmac_f32_e32 v183, v105, v241
	v_mfma_f32_32x32x16_bf16 v[2:17], v[54:57], v[166:169], v[2:17]
	v_max_f32_e32 v240, 0, v232
	v_fmac_f32_e32 v183, v106, v240
	v_max_f32_e32 v241, 0, v233
	v_fmac_f32_e32 v183, v107, v241
	v_max_f32_e32 v240, 0, v234
	v_fmac_f32_e32 v183, v108, v240
	v_max_f32_e32 v241, 0, v235
	v_fmac_f32_e32 v183, v109, v241
	v_mfma_f32_32x32x16_bf16 v[2:17], v[62:65], v[162:165], v[2:17]
	v_max_f32_e32 v240, 0, v236
	v_fmac_f32_e32 v183, v110, v240
	v_max_f32_e32 v241, 0, v237
	v_fmac_f32_e32 v183, v111, v241
	v_max_f32_e32 v240, 0, v238
	v_fmac_f32_e32 v183, v112, v240
	v_max_f32_e32 v241, 0, v239
	v_fmac_f32_e32 v183, v113, v241
	v_lshl_add_u64 v[242:243], v[190:191], 2, v[196:197]
	global_store_dword v[242:243], v183, off nt
	s_nop 1
	s_waitcnt vmcnt(9)
	s_barrier
	s_cmp_lt_u32 s32, 0x3000
	s_cbranch_scc0 .Lsc_nd0
	s_mul_i32 s98, s18, 0x2a00
	s_add_u32 s98, s98, s6
	s_addc_u32 s99, s7, 0
	s_add_u32 s98, s98, 0x2000
	s_addc_u32 s99, s99, 0
	s_add_i32 m0, s32, 0x0
	s_nop 0
	global_load_lds_dwordx4 v244, s[98:99]
.Lsc_nd0:
	ds_read_b128 v[154:157], v246 offset:4096
	ds_read_b128 v[150:153], v247 offset:4096
	ds_read_b128 v[146:149], v248 offset:4096
	ds_read_b128 v[158:161], v249 offset:4096
	v_mfma_f32_32x32x16_bf16 v[224:239], v[74:77], v[174:177], 0
	v_max_f32_e32 v240, 0, v2
	v_fma_f32 v183, v114, v240, 0
	v_max_f32_e32 v241, 0, v3
	v_fmac_f32_e32 v183, v115, v241
	v_max_f32_e32 v240, 0, v4
	v_fmac_f32_e32 v183, v116, v240
	v_max_f32_e32 v241, 0, v5
	v_fmac_f32_e32 v183, v117, v241
	v_mfma_f32_32x32x16_bf16 v[224:239], v[66:69], v[170:173], v[224:239]
	v_max_f32_e32 v240, 0, v6
	v_fmac_f32_e32 v183, v118, v240
	v_max_f32_e32 v241, 0, v7
	v_fmac_f32_e32 v183, v119, v241
	v_max_f32_e32 v240, 0, v8
	v_fmac_f32_e32 v183, v120, v240
	v_max_f32_e32 v241, 0, v9
	v_fmac_f32_e32 v183, v121, v241
	v_mfma_f32_32x32x16_bf16 v[224:239], v[70:73], v[166:169], v[224:239]
	v_max_f32_e32 v240, 0, v10
	v_fmac_f32_e32 v183, v122, v240
	v_max_f32_e32 v241, 0, v11
	v_fmac_f32_e32 v183, v123, v241
	v_max_f32_e32 v240, 0, v12
	v_fmac_f32_e32 v183, v124, v240
	v_max_f32_e32 v241, 0, v13
	v_fmac_f32_e32 v183, v125, v241
	v_mfma_f32_32x32x16_bf16 v[224:239], v[78:81], v[162:165], v[224:239]
	v_max_f32_e32 v240, 0, v14
	v_fmac_f32_e32 v183, v126, v240
	v_max_f32_e32 v241, 0, v15
	v_fmac_f32_e32 v183, v127, v241
	v_max_f32_e32 v240, 0, v16
	v_fmac_f32_e32 v183, v128, v240
	v_max_f32_e32 v241, 0, v17
	v_fmac_f32_e32 v183, v129, v241
	v_lshl_add_u64 v[242:243], v[192:193], 2, v[196:197]
	global_store_dword v[242:243], v183, off nt
	s_nop 1
	s_waitcnt lgkmcnt(0)
	v_mfma_f32_32x32x16_bf16 v[2:17], v[26:29], v[154:157], 0
	v_max_f32_e32 v240, 0, v224
	v_fma_f32 v183, v130, v240, 0
	v_max_f32_e32 v241, 0, v225
	v_fmac_f32_e32 v183, v131, v241
	v_max_f32_e32 v240, 0, v226
	v_fmac_f32_e32 v183, v132, v240
	v_max_f32_e32 v241, 0, v227
	v_fmac_f32_e32 v183, v133, v241
	v_mfma_f32_32x32x16_bf16 v[2:17], v[18:21], v[150:153], v[2:17]
	v_max_f32_e32 v240, 0, v228
	v_fmac_f32_e32 v183, v134, v240
	v_max_f32_e32 v241, 0, v229
	v_fmac_f32_e32 v183, v135, v241
	v_max_f32_e32 v240, 0, v230
	v_fmac_f32_e32 v183, v136, v240
	v_max_f32_e32 v241, 0, v231
	v_fmac_f32_e32 v183, v137, v241
	v_mfma_f32_32x32x16_bf16 v[2:17], v[22:25], v[146:149], v[2:17]
	v_max_f32_e32 v240, 0, v232
	v_fmac_f32_e32 v183, v138, v240
	v_max_f32_e32 v241, 0, v233
	v_fmac_f32_e32 v183, v139, v241
	v_max_f32_e32 v240, 0, v234
	v_fmac_f32_e32 v183, v140, v240
	v_max_f32_e32 v241, 0, v235
	v_fmac_f32_e32 v183, v141, v241
	v_mfma_f32_32x32x16_bf16 v[2:17], v[30:33], v[158:161], v[2:17]
	v_max_f32_e32 v240, 0, v236
	v_fmac_f32_e32 v183, v142, v240
	v_max_f32_e32 v241, 0, v237
	v_fmac_f32_e32 v183, v143, v241
	v_max_f32_e32 v240, 0, v238
	v_fmac_f32_e32 v183, v144, v240
	v_max_f32_e32 v241, 0, v239
	v_fmac_f32_e32 v183, v145, v241
	v_lshl_add_u64 v[242:243], v[194:195], 2, v[196:197]
	global_store_dword v[242:243], v183, off nt
	s_nop 1
	s_cmp_ge_i32 s15, s16
	s_cbranch_scc1 .LBB0_819
; #define MFMA(a, b, c) __builtin_amdgcn_mfma_f32_32x32x16_bf16((a), (b), (c), 0, 0, 0)
; DI void score_phase(const Params& p, char* smem) {
;     ...
;     for (int nt2 = nt_lo; nt2 < nt_hi; ++nt2) {
;       const int k0 = nt2 * 32;
;       const int kn = (nt2 + 1 < nt_hi) ? (k0 + 32) : k0;
; #pragma unroll
;       for (int st = 0; st < 4; ++st) bnx[st] = *(const bf16x8*)(Hb + (size_t)(kn + r) * HLD + 4096 + st * 16 + 8 * h);
; #pragma unroll
;       for (int rt = 0; rt < 4; ++rt) {
;         f32x16 acc;
; #pragma unroll
;         for (int e = 0; e < 16; ++e) acc[e] = 0.f;
; #pragma unroll
;         for (int st = 0; st < 4; ++st) acc = MFMA(af[rt][st], bfr[st], acc);
;         float s = 0.f;
; #pragma unroll
;         for (int e4 = 0; e4 < 4; ++e4) {
;           const f32x4 wv = *(const f32x4*)(wl + (2 * rt + h) * 16 + e4 * 4);
; #pragma unroll
;           for (int i = 0; i < 4; ++i) s += fmaxf(acc[e4 * 4 + i], 0.f) * wv[i];
;         }
;         const int row = (t0 + 2 * rt + h) - blk * 64;
;         __builtin_nontemporal_store(s, scb + (size_t)row * n + k0 + r);
;       }
; #pragma unroll
;       for (int st = 0; st < 4; ++st) bfr[st] = bnx[st];
	s_add_i32 s15, s15, 1
	s_add_i32 s17, s8, 32
	s_add_i32 s19, s8, 96
	s_add_i32 s18, s15, 2
	s_cmp_lt_i32 s18, s16
	s_cselect_b32 s18, s19, s8
	s_ashr_i32 s9, s8, 31
	v_lshl_add_u64 v[196:197], s[8:9], 2, v[186:187]
	s_mov_b32 s8, s17
	v_mfma_f32_32x32x16_bf16 v[224:239], v[42:45], v[154:157], 0
	v_max_f32_e32 v240, 0, v2
	v_fma_f32 v183, v82, v240, 0
	v_max_f32_e32 v241, 0, v3
	v_fmac_f32_e32 v183, v83, v241
	v_max_f32_e32 v240, 0, v4
	v_fmac_f32_e32 v183, v84, v240
	v_max_f32_e32 v241, 0, v5
	v_fmac_f32_e32 v183, v85, v241
	v_mfma_f32_32x32x16_bf16 v[224:239], v[34:37], v[150:153], v[224:239]
	v_max_f32_e32 v240, 0, v6
	v_fmac_f32_e32 v183, v86, v240
	v_max_f32_e32 v241, 0, v7
	v_fmac_f32_e32 v183, v87, v241
	v_max_f32_e32 v240, 0, v8
	v_fmac_f32_e32 v183, v88, v240
	v_max_f32_e32 v241, 0, v9
	v_fmac_f32_e32 v183, v89, v241
	v_mfma_f32_32x32x16_bf16 v[224:239], v[38:41], v[146:149], v[224:239]
	v_max_f32_e32 v240, 0, v10
	v_fmac_f32_e32 v183, v90, v240
	v_max_f32_e32 v241, 0, v11
	v_fmac_f32_e32 v183, v91, v241
	v_max_f32_e32 v240, 0, v12
	v_fmac_f32_e32 v183, v92, v240
	v_max_f32_e32 v241, 0, v13
	v_fmac_f32_e32 v183, v93, v241
	v_mfma_f32_32x32x16_bf16 v[224:239], v[46:49], v[158:161], v[224:239]
	v_max_f32_e32 v240, 0, v14
	v_fmac_f32_e32 v183, v94, v240
	v_max_f32_e32 v241, 0, v15
	v_fmac_f32_e32 v183, v95, v241
	v_max_f32_e32 v240, 0, v16
	v_fmac_f32_e32 v183, v96, v240
	v_max_f32_e32 v241, 0, v17
	v_fmac_f32_e32 v183, v97, v241
	v_lshl_add_u64 v[242:243], v[188:189], 2, v[196:197]
	global_store_dword v[242:243], v183, off nt
	s_nop 1
	v_mfma_f32_32x32x16_bf16 v[2:17], v[58:61], v[154:157], 0
	v_max_f32_e32 v240, 0, v224
	v_fma_f32 v183, v98, v240, 0
	v_max_f32_e32 v241, 0, v225
	v_fmac_f32_e32 v183, v99, v241
	v_max_f32_e32 v240, 0, v226
	v_fmac_f32_e32 v183, v100, v240
	v_max_f32_e32 v241, 0, v227
	v_fmac_f32_e32 v183, v101, v241
	v_mfma_f32_32x32x16_bf16 v[2:17], v[50:53], v[150:153], v[2:17]
	v_max_f32_e32 v240, 0, v228
	v_fmac_f32_e32 v183, v102, v240
	v_max_f32_e32 v241, 0, v229
	v_fmac_f32_e32 v183, v103, v241
	v_max_f32_e32 v240, 0, v230
	v_fmac_f32_e32 v183, v104, v240
	v_max_f32_e32 v241, 0, v231
	v_fmac_f32_e32 v183, v105, v241
	v_mfma_f32_32x32x16_bf16 v[2:17], v[54:57], v[146:149], v[2:17]
	v_max_f32_e32 v240, 0, v232
	v_fmac_f32_e32 v183, v106, v240
	v_max_f32_e32 v241, 0, v233
	v_fmac_f32_e32 v183, v107, v241
	v_max_f32_e32 v240, 0, v234
	v_fmac_f32_e32 v183, v108, v240
	v_max_f32_e32 v241, 0, v235
	v_fmac_f32_e32 v183, v109, v241
	v_mfma_f32_32x32x16_bf16 v[2:17], v[62:65], v[158:161], v[2:17]
	v_max_f32_e32 v240, 0, v236
	v_fmac_f32_e32 v183, v110, v240
	v_max_f32_e32 v241, 0, v237
	v_fmac_f32_e32 v183, v111, v241
	v_max_f32_e32 v240, 0, v238
	v_fmac_f32_e32 v183, v112, v240
	v_max_f32_e32 v241, 0, v239
	v_fmac_f32_e32 v183, v113, v241
	v_lshl_add_u64 v[242:243], v[190:191], 2, v[196:197]
	global_store_dword v[242:243], v183, off nt
	s_nop 1
	s_waitcnt vmcnt(9)
	s_barrier
	s_cmp_lt_u32 s32, 0x3000
	s_cbranch_scc0 .Lsc_nd1
	s_mul_i32 s98, s18, 0x2a00
	s_add_u32 s98, s98, s6
	s_addc_u32 s99, s7, 0
	s_add_u32 s98, s98, 0x2000
	s_addc_u32 s99, s99, 0
	s_add_i32 m0, s32, 0x1000
	s_nop 0
	global_load_lds_dwordx4 v244, s[98:99]
.Lsc_nd1:
	ds_read_b128 v[204:207], v246 offset:8192
	ds_read_b128 v[208:211], v247 offset:8192
	ds_read_b128 v[212:215], v248 offset:8192
	ds_read_b128 v[250:253], v249 offset:8192
	v_mfma_f32_32x32x16_bf16 v[224:239], v[74:77], v[154:157], 0
	v_max_f32_e32 v240, 0, v2
	v_fma_f32 v183, v114, v240, 0
	v_max_f32_e32 v241, 0, v3
	v_fmac_f32_e32 v183, v115, v241
	v_max_f32_e32 v240, 0, v4
	v_fmac_f32_e32 v183, v116, v240
	v_max_f32_e32 v241, 0, v5
	v_fmac_f32_e32 v183, v117, v241
	v_mfma_f32_32x32x16_bf16 v[224:239], v[66:69], v[150:153], v[224:239]
	v_max_f32_e32 v240, 0, v6
	v_fmac_f32_e32 v183, v118, v240
	v_max_f32_e32 v241, 0, v7
	v_fmac_f32_e32 v183, v119, v241
	v_max_f32_e32 v240, 0, v8
	v_fmac_f32_e32 v183, v120, v240
	v_max_f32_e32 v241, 0, v9
	v_fmac_f32_e32 v183, v121, v241
	v_mfma_f32_32x32x16_bf16 v[224:239], v[70:73], v[146:149], v[224:239]
	v_max_f32_e32 v240, 0, v10
	v_fmac_f32_e32 v183, v122, v240
	v_max_f32_e32 v241, 0, v11
	v_fmac_f32_e32 v183, v123, v241
	v_max_f32_e32 v240, 0, v12
	v_fmac_f32_e32 v183, v124, v240
	v_max_f32_e32 v241, 0, v13
	v_fmac_f32_e32 v183, v125, v241
	v_mfma_f32_32x32x16_bf16 v[224:239], v[78:81], v[158:161], v[224:239]
	v_max_f32_e32 v240, 0, v14
	v_fmac_f32_e32 v183, v126, v240
	v_max_f32_e32 v241, 0, v15
	v_fmac_f32_e32 v183, v127, v241
	v_max_f32_e32 v240, 0, v16
	v_fmac_f32_e32 v183, v128, v240
	v_max_f32_e32 v241, 0, v17
	v_fmac_f32_e32 v183, v129, v241
	v_lshl_add_u64 v[242:243], v[192:193], 2, v[196:197]
	global_store_dword v[242:243], v183, off nt
	s_nop 1
	s_waitcnt lgkmcnt(0)
	v_mfma_f32_32x32x16_bf16 v[2:17], v[26:29], v[204:207], 0
	v_max_f32_e32 v240, 0, v224
	v_fma_f32 v183, v130, v240, 0
	v_max_f32_e32 v241, 0, v225
	v_fmac_f32_e32 v183, v131, v241
	v_max_f32_e32 v240, 0, v226
	v_fmac_f32_e32 v183, v132, v240
	v_max_f32_e32 v241, 0, v227
	v_fmac_f32_e32 v183, v133, v241
	v_mfma_f32_32x32x16_bf16 v[2:17], v[18:21], v[208:211], v[2:17]
	v_max_f32_e32 v240, 0, v228
	v_fmac_f32_e32 v183, v134, v240
	v_max_f32_e32 v241, 0, v229
	v_fmac_f32_e32 v183, v135, v241
	v_max_f32_e32 v240, 0, v230
	v_fmac_f32_e32 v183, v136, v240
	v_max_f32_e32 v241, 0, v231
	v_fmac_f32_e32 v183, v137, v241
	v_mfma_f32_32x32x16_bf16 v[2:17], v[22:25], v[212:215], v[2:17]
	v_max_f32_e32 v240, 0, v232
	v_fmac_f32_e32 v183, v138, v240
	v_max_f32_e32 v241, 0, v233
	v_fmac_f32_e32 v183, v139, v241
	v_max_f32_e32 v240, 0, v234
	v_fmac_f32_e32 v183, v140, v240
	v_max_f32_e32 v241, 0, v235
	v_fmac_f32_e32 v183, v141, v241
	v_mfma_f32_32x32x16_bf16 v[2:17], v[30:33], v[250:253], v[2:17]
	v_max_f32_e32 v240, 0, v236
	v_fmac_f32_e32 v183, v142, v240
	v_max_f32_e32 v241, 0, v237
	v_fmac_f32_e32 v183, v143, v241
	v_max_f32_e32 v240, 0, v238
	v_fmac_f32_e32 v183, v144, v240
	v_max_f32_e32 v241, 0, v239
	v_fmac_f32_e32 v183, v145, v241
	v_lshl_add_u64 v[242:243], v[194:195], 2, v[196:197]
	global_store_dword v[242:243], v183, off nt
	s_nop 1
	s_cmp_ge_i32 s15, s16
	s_cbranch_scc1 .LBB0_819
; #define MFMA(a, b, c) __builtin_amdgcn_mfma_f32_32x32x16_bf16((a), (b), (c), 0, 0, 0)
; DI void score_phase(const Params& p, char* smem) {
;     ...
;     for (int nt2 = nt_lo; nt2 < nt_hi; ++nt2) {
;       const int k0 = nt2 * 32;
;       const int kn = (nt2 + 1 < nt_hi) ? (k0 + 32) : k0;
; #pragma unroll
;       for (int st = 0; st < 4; ++st) bnx[st] = *(const bf16x8*)(Hb + (size_t)(kn + r) * HLD + 4096 + st * 16 + 8 * h);
; #pragma unroll
;       for (int rt = 0; rt < 4; ++rt) {
;         f32x16 acc;
; #pragma unroll
;         for (int e = 0; e < 16; ++e) acc[e] = 0.f;
; #pragma unroll
;         for (int st = 0; st < 4; ++st) acc = MFMA(af[rt][st], bfr[st], acc);
;         float s = 0.f;
; #pragma unroll
;         for (int e4 = 0; e4 < 4; ++e4) {
;           const f32x4 wv = *(const f32x4*)(wl + (2 * rt + h) * 16 + e4 * 4);
; #pragma unroll
;           for (int i = 0; i < 4; ++i) s += fmaxf(acc[e4 * 4 + i], 0.f) * wv[i];
;         }
;         const int row = (t0 + 2 * rt + h) - blk * 64;
;         __builtin_nontemporal_store(s, scb + (size_t)row * n + k0 + r);
;       }
; #pragma unroll
;       for (int st = 0; st < 4; ++st) bfr[st] = bnx[st];
	s_add_i32 s15, s15, 1
	s_add_i32 s17, s8, 32
	s_add_i32 s19, s8, 96
	s_add_i32 s18, s15, 2
	s_cmp_lt_i32 s18, s16
	s_cselect_b32 s18, s19, s8
	s_ashr_i32 s9, s8, 31
	v_lshl_add_u64 v[196:197], s[8:9], 2, v[186:187]
	s_mov_b32 s8, s17
	v_mfma_f32_32x32x16_bf16 v[224:239], v[42:45], v[204:207], 0
	v_max_f32_e32 v240, 0, v2
	v_fma_f32 v183, v82, v240, 0
	v_max_f32_e32 v241, 0, v3
	v_fmac_f32_e32 v183, v83, v241
	v_max_f32_e32 v240, 0, v4
	v_fmac_f32_e32 v183, v84, v240
	v_max_f32_e32 v241, 0, v5
	v_fmac_f32_e32 v183, v85, v241
	v_mfma_f32_32x32x16_bf16 v[224:239], v[34:37], v[208:211], v[224:239]
	v_max_f32_e32 v240, 0, v6
	v_fmac_f32_e32 v183, v86, v240
	v_max_f32_e32 v241, 0, v7
	v_fmac_f32_e32 v183, v87, v241
	v_max_f32_e32 v240, 0, v8
	v_fmac_f32_e32 v183, v88, v240
	v_max_f32_e32 v241, 0, v9
	v_fmac_f32_e32 v183, v89, v241
	v_mfma_f32_32x32x16_bf16 v[224:239], v[38:41], v[212:215], v[224:239]
	v_max_f32_e32 v240, 0, v10
	v_fmac_f32_e32 v183, v90, v240
	v_max_f32_e32 v241, 0, v11
	v_fmac_f32_e32 v183, v91, v241
	v_max_f32_e32 v240, 0, v12
	v_fmac_f32_e32 v183, v92, v240
	v_max_f32_e32 v241, 0, v13
	v_fmac_f32_e32 v183, v93, v241
	v_mfma_f32_32x32x16_bf16 v[224:239], v[46:49], v[250:253], v[224:239]
	v_max_f32_e32 v240, 0, v14
	v_fmac_f32_e32 v183, v94, v240
	v_max_f32_e32 v241, 0, v15
	v_fmac_f32_e32 v183, v95, v241
	v_max_f32_e32 v240, 0, v16
	v_fmac_f32_e32 v183, v96, v240
	v_max_f32_e32 v241, 0, v17
	v_fmac_f32_e32 v183, v97, v241
	v_lshl_add_u64 v[242:243], v[188:189], 2, v[196:197]
	global_store_dword v[242:243], v183, off nt
	s_nop 1
	v_mfma_f32_32x32x16_bf16 v[2:17], v[58:61], v[204:207], 0
	v_max_f32_e32 v240, 0, v224
	v_fma_f32 v183, v98, v240, 0
	v_max_f32_e32 v241, 0, v225
	v_fmac_f32_e32 v183, v99, v241
	v_max_f32_e32 v240, 0, v226
	v_fmac_f32_e32 v183, v100, v240
	v_max_f32_e32 v241, 0, v227
	v_fmac_f32_e32 v183, v101, v241
	v_mfma_f32_32x32x16_bf16 v[2:17], v[50:53], v[208:211], v[2:17]
	v_max_f32_e32 v240, 0, v228
	v_fmac_f32_e32 v183, v102, v240
	v_max_f32_e32 v241, 0, v229
	v_fmac_f32_e32 v183, v103, v241
	v_max_f32_e32 v240, 0, v230
	v_fmac_f32_e32 v183, v104, v240
	v_max_f32_e32 v241, 0, v231
	v_fmac_f32_e32 v183, v105, v241
	v_mfma_f32_32x32x16_bf16 v[2:17], v[54:57], v[212:215], v[2:17]
	v_max_f32_e32 v240, 0, v232
	v_fmac_f32_e32 v183, v106, v240
	v_max_f32_e32 v241, 0, v233
	v_fmac_f32_e32 v183, v107, v241
	v_max_f32_e32 v240, 0, v234
	v_fmac_f32_e32 v183, v108, v240
	v_max_f32_e32 v241, 0, v235
	v_fmac_f32_e32 v183, v109, v241
	v_mfma_f32_32x32x16_bf16 v[2:17], v[62:65], v[250:253], v[2:17]
	v_max_f32_e32 v240, 0, v236
	v_fmac_f32_e32 v183, v110, v240
	v_max_f32_e32 v241, 0, v237
	v_fmac_f32_e32 v183, v111, v241
	v_max_f32_e32 v240, 0, v238
	v_fmac_f32_e32 v183, v112, v240
	v_max_f32_e32 v241, 0, v239
	v_fmac_f32_e32 v183, v113, v241
	v_lshl_add_u64 v[242:243], v[190:191], 2, v[196:197]
	global_store_dword v[242:243], v183, off nt
	s_nop 1
	s_waitcnt vmcnt(9)
	s_barrier
	s_cmp_lt_u32 s32, 0x3000
	s_cbranch_scc0 .Lsc_nd2
	s_mul_i32 s98, s18, 0x2a00
	s_add_u32 s98, s98, s6
	s_addc_u32 s99, s7, 0
	s_add_u32 s98, s98, 0x2000
	s_addc_u32 s99, s99, 0
	s_add_i32 m0, s32, 0x2000
	s_nop 0
	global_load_lds_dwordx4 v244, s[98:99]
.Lsc_nd2:
	ds_read_b128 v[174:177], v246 offset:0
	ds_read_b128 v[170:173], v247 offset:0
	ds_read_b128 v[166:169], v248 offset:0
	ds_read_b128 v[162:165], v249 offset:0
	v_mfma_f32_32x32x16_bf16 v[224:239], v[74:77], v[204:207], 0
	v_max_f32_e32 v240, 0, v2
	v_fma_f32 v183, v114, v240, 0
	v_max_f32_e32 v241, 0, v3
	v_fmac_f32_e32 v183, v115, v241
	v_max_f32_e32 v240, 0, v4
	v_fmac_f32_e32 v183, v116, v240
	v_max_f32_e32 v241, 0, v5
	v_fmac_f32_e32 v183, v117, v241
	v_mfma_f32_32x32x16_bf16 v[224:239], v[66:69], v[208:211], v[224:239]
	v_max_f32_e32 v240, 0, v6
	v_fmac_f32_e32 v183, v118, v240
	v_max_f32_e32 v241, 0, v7
	v_fmac_f32_e32 v183, v119, v241
	v_max_f32_e32 v240, 0, v8
	v_fmac_f32_e32 v183, v120, v240
	v_max_f32_e32 v241, 0, v9
	v_fmac_f32_e32 v183, v121, v241
	v_mfma_f32_32x32x16_bf16 v[224:239], v[70:73], v[212:215], v[224:239]
	v_max_f32_e32 v240, 0, v10
	v_fmac_f32_e32 v183, v122, v240
	v_max_f32_e32 v241, 0, v11
	v_fmac_f32_e32 v183, v123, v241
	v_max_f32_e32 v240, 0, v12
	v_fmac_f32_e32 v183, v124, v240
	v_max_f32_e32 v241, 0, v13
	v_fmac_f32_e32 v183, v125, v241
	v_mfma_f32_32x32x16_bf16 v[224:239], v[78:81], v[250:253], v[224:239]
	v_max_f32_e32 v240, 0, v14
	v_fmac_f32_e32 v183, v126, v240
	v_max_f32_e32 v241, 0, v15
	v_fmac_f32_e32 v183, v127, v241
	v_max_f32_e32 v240, 0, v16
	v_fmac_f32_e32 v183, v128, v240
	v_max_f32_e32 v241, 0, v17
	v_fmac_f32_e32 v183, v129, v241
	v_lshl_add_u64 v[242:243], v[192:193], 2, v[196:197]
	global_store_dword v[242:243], v183, off nt
	s_nop 1
	s_waitcnt lgkmcnt(0)
	v_mfma_f32_32x32x16_bf16 v[2:17], v[26:29], v[174:177], 0
	v_max_f32_e32 v240, 0, v224
	v_fma_f32 v183, v130, v240, 0
	v_max_f32_e32 v241, 0, v225
	v_fmac_f32_e32 v183, v131, v241
	v_max_f32_e32 v240, 0, v226
	v_fmac_f32_e32 v183, v132, v240
	v_max_f32_e32 v241, 0, v227
	v_fmac_f32_e32 v183, v133, v241
	v_mfma_f32_32x32x16_bf16 v[2:17], v[18:21], v[170:173], v[2:17]
	v_max_f32_e32 v240, 0, v228
	v_fmac_f32_e32 v183, v134, v240
	v_max_f32_e32 v241, 0, v229
	v_fmac_f32_e32 v183, v135, v241
	v_max_f32_e32 v240, 0, v230
	v_fmac_f32_e32 v183, v136, v240
	v_max_f32_e32 v241, 0, v231
	v_fmac_f32_e32 v183, v137, v241
	v_mfma_f32_32x32x16_bf16 v[2:17], v[22:25], v[166:169], v[2:17]
	v_max_f32_e32 v240, 0, v232
	v_fmac_f32_e32 v183, v138, v240
	v_max_f32_e32 v241, 0, v233
	v_fmac_f32_e32 v183, v139, v241
	v_max_f32_e32 v240, 0, v234
	v_fmac_f32_e32 v183, v140, v240
	v_max_f32_e32 v241, 0, v235
	v_fmac_f32_e32 v183, v141, v241
	v_mfma_f32_32x32x16_bf16 v[2:17], v[30:33], v[162:165], v[2:17]
	v_max_f32_e32 v240, 0, v236
	v_fmac_f32_e32 v183, v142, v240
	v_max_f32_e32 v241, 0, v237
	v_fmac_f32_e32 v183, v143, v241
	v_max_f32_e32 v240, 0, v238
	v_fmac_f32_e32 v183, v144, v240
	v_max_f32_e32 v241, 0, v239
	v_fmac_f32_e32 v183, v145, v241
	v_lshl_add_u64 v[242:243], v[194:195], 2, v[196:197]
	global_store_dword v[242:243], v183, off nt
	s_nop 1
	s_cmp_ge_i32 s15, s16
	s_cbranch_scc0 .LBB0_822
	s_branch .LBB0_819
